# attention block selection: the four top-16 rank loops hand-written (pipelined LDS row reads, compare results shifted into per-lane bit masks, popcount)
# speedup vs baseline: 1.0080x; 1.0080x over previous
; DI void attn_unit(LAS unsigned char* lds, const Args& a, int bg, int qt) {
;     ...
;         for (int it = 0; it < 4; ++it) { const int q = (tid >> 5) + 16 * it;
;             float v = 0.f;
; #pragma unroll
;             for (int h = 0; h < 4; ++h) { const int hq = h * 64 + q; const float sc = SCL[hq * 3 + (j >> 4)]; v += IMP[hq * IMP_PITCH + j] * sc + ((j == 16) ? SCL[hq * 3 + 2] : 0.f); }
;             const bool forced = (j == 0) || (j == qt) || (j == qt - 1);
;             v = forced ? 1e4f : (j > qt ? -1.0f : v);
;             VAL[q * 32 + j] = v; }
.LBB0_817:
	ds_read_b32 v35, v193
	ds_read_b32 v38, v240
	v_mov_b32_e32 v34, 0
	v_mov_b32_e32 v39, 0
	s_and_saveexec_b64 s[10:11], s[4:5]
	ds_read_b32 v39, v192 offset:8
	s_or_b64 exec, exec, s[10:11]
	ds_read_b32 v40, v195
	ds_read_b32 v41, v240 offset:8448
	s_and_saveexec_b64 s[10:11], s[4:5]
	ds_read_b32 v34, v194 offset:8
	s_or_b64 exec, exec, s[10:11]
	ds_read_b32 v43, v197
	ds_read_b32 v44, v240 offset:16896
	v_mov_b32_e32 v42, 0
	v_mov_b32_e32 v45, 0
	s_and_saveexec_b64 s[10:11], s[4:5]
	ds_read_b32 v45, v196 offset:8
	s_or_b64 exec, exec, s[10:11]
	ds_read_b32 v46, v199
	ds_read_b32 v47, v240 offset:25344
	s_and_saveexec_b64 s[10:11], s[4:5]
	ds_read_b32 v42, v198 offset:8
	s_or_b64 exec, exec, s[10:11]
	s_waitcnt lgkmcnt(6)
	v_fmac_f32_e32 v39, v35, v38
	v_add_f32_e32 v35, 0, v39
	s_waitcnt lgkmcnt(4)
	v_fmac_f32_e32 v34, v40, v41
	v_add_f32_e32 v34, v35, v34
	s_waitcnt lgkmcnt(2)
	v_fmac_f32_e32 v45, v43, v44
	v_add_f32_e32 v34, v34, v45
	v_cmp_eq_u32_e32 vcc, s73, v98
	s_add_i32 s10, s73, -1
	s_waitcnt lgkmcnt(0)
	v_fmac_f32_e32 v42, v46, v47
	s_or_b64 s[12:13], s[6:7], vcc
	v_cmp_eq_u32_e64 s[10:11], s10, v98
	v_add_f32_e32 v34, v34, v42
	v_cmp_lt_u32_e32 vcc, s73, v98
	s_or_b64 s[10:11], s[12:13], s[10:11]
	v_mov_b32_e32 v39, 0
	v_cndmask_b32_e64 v34, v34, -1.0, vcc
	v_cndmask_b32_e64 v34, v34, v241, s[10:11]
	ds_write_b32 v224, v34
	ds_read_b32 v35, v201
	ds_read_b32 v38, v240 offset:2112
	v_mov_b32_e32 v34, 0
	s_and_saveexec_b64 s[12:13], s[4:5]
	ds_read_b32 v39, v200 offset:8
	s_or_b64 exec, exec, s[12:13]
	ds_read_b32 v40, v203
	ds_read_b32 v41, v240 offset:10560
	s_and_saveexec_b64 s[12:13], s[4:5]
	ds_read_b32 v34, v202 offset:8
	s_or_b64 exec, exec, s[12:13]
	ds_read_b32 v43, v205
	ds_read_b32 v44, v240 offset:19008
	v_mov_b32_e32 v42, 0
	v_mov_b32_e32 v45, 0
	s_and_saveexec_b64 s[12:13], s[4:5]
	ds_read_b32 v45, v204 offset:8
	s_or_b64 exec, exec, s[12:13]
	ds_read_b32 v46, v207
	ds_read_b32 v47, v240 offset:27456
	s_and_saveexec_b64 s[12:13], s[4:5]
	ds_read_b32 v42, v206 offset:8
	s_or_b64 exec, exec, s[12:13]
	s_waitcnt lgkmcnt(6)
	v_fmac_f32_e32 v39, v35, v38
	v_add_f32_e32 v35, 0, v39
	s_waitcnt lgkmcnt(4)
	v_fmac_f32_e32 v34, v40, v41
	v_add_f32_e32 v34, v35, v34
	s_waitcnt lgkmcnt(2)
	v_fmac_f32_e32 v45, v43, v44
	v_add_f32_e32 v34, v34, v45
	s_waitcnt lgkmcnt(0)
	v_fmac_f32_e32 v42, v46, v47
	v_add_f32_e32 v34, v34, v42
	v_cndmask_b32_e64 v34, v34, -1.0, vcc
	v_cndmask_b32_e64 v34, v34, v241, s[10:11]
	ds_write_b32 v226, v34
	ds_read_b32 v35, v209
	ds_read_b32 v38, v240 offset:4224
	v_mov_b32_e32 v34, 0
	v_mov_b32_e32 v39, 0
	s_and_saveexec_b64 s[12:13], s[4:5]
	ds_read_b32 v39, v208 offset:8
	s_or_b64 exec, exec, s[12:13]
	ds_read_b32 v40, v211
	ds_read_b32 v41, v240 offset:12672
	s_and_saveexec_b64 s[12:13], s[4:5]
	ds_read_b32 v34, v210 offset:8
	s_or_b64 exec, exec, s[12:13]
	ds_read_b32 v43, v213
	ds_read_b32 v44, v240 offset:21120
	v_mov_b32_e32 v42, 0
	v_mov_b32_e32 v45, 0
	s_and_saveexec_b64 s[12:13], s[4:5]
	ds_read_b32 v45, v212 offset:8
	s_or_b64 exec, exec, s[12:13]
	ds_read_b32 v46, v215
	ds_read_b32 v47, v240 offset:29568
	s_and_saveexec_b64 s[12:13], s[4:5]
	ds_read_b32 v42, v214 offset:8
	s_or_b64 exec, exec, s[12:13]
	s_waitcnt lgkmcnt(6)
	v_fmac_f32_e32 v39, v35, v38
	v_add_f32_e32 v35, 0, v39
	s_waitcnt lgkmcnt(4)
	v_fmac_f32_e32 v34, v40, v41
	v_add_f32_e32 v34, v35, v34
	s_waitcnt lgkmcnt(2)
	v_fmac_f32_e32 v45, v43, v44
	v_add_f32_e32 v34, v34, v45
	s_waitcnt lgkmcnt(0)
	v_fmac_f32_e32 v42, v46, v47
	v_add_f32_e32 v34, v34, v42
	v_cndmask_b32_e64 v34, v34, -1.0, vcc
	v_cndmask_b32_e64 v34, v34, v241, s[10:11]
	ds_write_b32 v228, v34
	ds_read_b32 v35, v217
	ds_read_b32 v38, v240 offset:6336
	v_mov_b32_e32 v34, 0
	v_mov_b32_e32 v39, 0
	s_and_saveexec_b64 s[12:13], s[4:5]
	ds_read_b32 v39, v216 offset:8
	s_or_b64 exec, exec, s[12:13]
	ds_read_b32 v40, v219
	ds_read_b32 v41, v240 offset:14784
	s_and_saveexec_b64 s[12:13], s[4:5]
	ds_read_b32 v34, v218 offset:8
	s_or_b64 exec, exec, s[12:13]
	ds_read_b32 v43, v221
	ds_read_b32 v44, v240 offset:23232
	v_mov_b32_e32 v42, 0
	v_mov_b32_e32 v45, 0
	s_and_saveexec_b64 s[12:13], s[4:5]
	ds_read_b32 v45, v220 offset:8
	s_or_b64 exec, exec, s[12:13]
	ds_read_b32 v46, v223
	ds_read_b32 v47, v240 offset:31680
	s_and_saveexec_b64 s[12:13], s[4:5]
	ds_read_b32 v42, v222 offset:8
	s_or_b64 exec, exec, s[12:13]
	s_waitcnt lgkmcnt(6)
	v_fmac_f32_e32 v39, v35, v38
	v_add_f32_e32 v35, 0, v39
	s_waitcnt lgkmcnt(4)
	v_fmac_f32_e32 v34, v40, v41
	v_add_f32_e32 v34, v35, v34
	s_waitcnt lgkmcnt(2)
	v_fmac_f32_e32 v45, v43, v44
	v_add_f32_e32 v34, v34, v45
	s_waitcnt lgkmcnt(0)
	v_fmac_f32_e32 v42, v46, v47
	v_add_f32_e32 v34, v34, v42
	v_cndmask_b32_e64 v34, v34, -1.0, vcc
	v_cndmask_b32_e64 v34, v34, v241, s[10:11]
	ds_write_b32 v230, v34
	s_waitcnt lgkmcnt(0)
	s_barrier
; DI void attn_unit(LAS unsigned char* lds, const Args& a, int bg, int qt) {
;     ...
;         for (int it = 0; it < 4; ++it) { const int q = (tid >> 5) + 16 * it;
;             const float v = VAL[q * 32 + j]; int cnt = 0;
; #pragma unroll 8
;             for (int jj = 0; jj < 32; ++jj) { const float ov = VAL[q * 32 + jj]; cnt += ((ov > v) || (ov == v && jj < j)) ? 1 : 0; }
;             const unsigned long long bal = __ballot(cnt < 16);
	v_add_u32_e32 v65, 0x18400, v234
	ds_read_b32 v34, v224
	ds_read_b128 v[40:43], v65
	ds_read_b128 v[44:47], v65 offset:16
	ds_read_b128 v[48:51], v65 offset:32
	ds_read_b128 v[52:55], v65 offset:48
	ds_read_b128 v[56:59], v65 offset:64
	ds_read_b128 v[60:63], v65 offset:80
	v_mov_b32_e32 v35, 0
	v_mov_b32_e32 v38, 0
	s_waitcnt lgkmcnt(5)
	v_cmp_gt_f32_e64 s[10:11], v40, v34
	v_cmp_eq_f32_e64 s[12:13], v40, v34
	v_cmp_gt_f32_e64 s[16:17], v41, v34
	v_cmp_eq_f32_e64 s[18:19], v41, v34
	v_addc_co_u32_e64 v35, s[20:21], v35, v35, s[10:11]
	v_addc_co_u32_e64 v38, s[20:21], v38, v38, s[12:13]
	v_addc_co_u32_e64 v35, s[20:21], v35, v35, s[16:17]
	v_addc_co_u32_e64 v38, s[20:21], v38, v38, s[18:19]
	v_cmp_gt_f32_e64 s[10:11], v42, v34
	v_cmp_eq_f32_e64 s[12:13], v42, v34
	v_cmp_gt_f32_e64 s[16:17], v43, v34
	v_cmp_eq_f32_e64 s[18:19], v43, v34
	v_addc_co_u32_e64 v35, s[20:21], v35, v35, s[10:11]
	v_addc_co_u32_e64 v38, s[20:21], v38, v38, s[12:13]
	v_addc_co_u32_e64 v35, s[20:21], v35, v35, s[16:17]
	v_addc_co_u32_e64 v38, s[20:21], v38, v38, s[18:19]
	ds_read_b128 v[40:43], v65 offset:96
	s_waitcnt lgkmcnt(5)
	v_cmp_gt_f32_e64 s[10:11], v44, v34
	v_cmp_eq_f32_e64 s[12:13], v44, v34
	v_cmp_gt_f32_e64 s[16:17], v45, v34
	v_cmp_eq_f32_e64 s[18:19], v45, v34
	v_addc_co_u32_e64 v35, s[20:21], v35, v35, s[10:11]
	v_addc_co_u32_e64 v38, s[20:21], v38, v38, s[12:13]
	v_addc_co_u32_e64 v35, s[20:21], v35, v35, s[16:17]
	v_addc_co_u32_e64 v38, s[20:21], v38, v38, s[18:19]
	v_cmp_gt_f32_e64 s[10:11], v46, v34
	v_cmp_eq_f32_e64 s[12:13], v46, v34
	v_cmp_gt_f32_e64 s[16:17], v47, v34
	v_cmp_eq_f32_e64 s[18:19], v47, v34
	v_addc_co_u32_e64 v35, s[20:21], v35, v35, s[10:11]
	v_addc_co_u32_e64 v38, s[20:21], v38, v38, s[12:13]
	v_addc_co_u32_e64 v35, s[20:21], v35, v35, s[16:17]
	v_addc_co_u32_e64 v38, s[20:21], v38, v38, s[18:19]
	ds_read_b128 v[44:47], v65 offset:112
	s_waitcnt lgkmcnt(5)
	v_cmp_gt_f32_e64 s[10:11], v48, v34
	v_cmp_eq_f32_e64 s[12:13], v48, v34
	v_cmp_gt_f32_e64 s[16:17], v49, v34
	v_cmp_eq_f32_e64 s[18:19], v49, v34
	v_addc_co_u32_e64 v35, s[20:21], v35, v35, s[10:11]
	v_addc_co_u32_e64 v38, s[20:21], v38, v38, s[12:13]
	v_addc_co_u32_e64 v35, s[20:21], v35, v35, s[16:17]
	v_addc_co_u32_e64 v38, s[20:21], v38, v38, s[18:19]
	v_cmp_gt_f32_e64 s[10:11], v50, v34
	v_cmp_eq_f32_e64 s[12:13], v50, v34
	v_cmp_gt_f32_e64 s[16:17], v51, v34
	v_cmp_eq_f32_e64 s[18:19], v51, v34
	v_addc_co_u32_e64 v35, s[20:21], v35, v35, s[10:11]
	v_addc_co_u32_e64 v38, s[20:21], v38, v38, s[12:13]
	v_addc_co_u32_e64 v35, s[20:21], v35, v35, s[16:17]
	v_addc_co_u32_e64 v38, s[20:21], v38, v38, s[18:19]
	ds_read_b32 v64, v226
	ds_read_b128 v[48:51], v65 offset:2048
	s_waitcnt lgkmcnt(6)
	v_cmp_gt_f32_e64 s[10:11], v52, v34
	v_cmp_eq_f32_e64 s[12:13], v52, v34
	v_cmp_gt_f32_e64 s[16:17], v53, v34
	v_cmp_eq_f32_e64 s[18:19], v53, v34
	v_addc_co_u32_e64 v35, s[20:21], v35, v35, s[10:11]
	v_addc_co_u32_e64 v38, s[20:21], v38, v38, s[12:13]
	v_addc_co_u32_e64 v35, s[20:21], v35, v35, s[16:17]
	v_addc_co_u32_e64 v38, s[20:21], v38, v38, s[18:19]
	v_cmp_gt_f32_e64 s[10:11], v54, v34
	v_cmp_eq_f32_e64 s[12:13], v54, v34
	v_cmp_gt_f32_e64 s[16:17], v55, v34
	v_cmp_eq_f32_e64 s[18:19], v55, v34
	v_addc_co_u32_e64 v35, s[20:21], v35, v35, s[10:11]
	v_addc_co_u32_e64 v38, s[20:21], v38, v38, s[12:13]
	v_addc_co_u32_e64 v35, s[20:21], v35, v35, s[16:17]
	v_addc_co_u32_e64 v38, s[20:21], v38, v38, s[18:19]
	ds_read_b128 v[52:55], v65 offset:2064
	s_waitcnt lgkmcnt(6)
	v_cmp_gt_f32_e64 s[10:11], v56, v34
	v_cmp_eq_f32_e64 s[12:13], v56, v34
	v_cmp_gt_f32_e64 s[16:17], v57, v34
	v_cmp_eq_f32_e64 s[18:19], v57, v34
	v_addc_co_u32_e64 v35, s[20:21], v35, v35, s[10:11]
	v_addc_co_u32_e64 v38, s[20:21], v38, v38, s[12:13]
	v_addc_co_u32_e64 v35, s[20:21], v35, v35, s[16:17]
	v_addc_co_u32_e64 v38, s[20:21], v38, v38, s[18:19]
	v_cmp_gt_f32_e64 s[10:11], v58, v34
	v_cmp_eq_f32_e64 s[12:13], v58, v34
	v_cmp_gt_f32_e64 s[16:17], v59, v34
	v_cmp_eq_f32_e64 s[18:19], v59, v34
	v_addc_co_u32_e64 v35, s[20:21], v35, v35, s[10:11]
	v_addc_co_u32_e64 v38, s[20:21], v38, v38, s[12:13]
	v_addc_co_u32_e64 v35, s[20:21], v35, v35, s[16:17]
	v_addc_co_u32_e64 v38, s[20:21], v38, v38, s[18:19]
	ds_read_b128 v[56:59], v65 offset:2080
	s_waitcnt lgkmcnt(6)
	v_cmp_gt_f32_e64 s[10:11], v60, v34
	v_cmp_eq_f32_e64 s[12:13], v60, v34
	v_cmp_gt_f32_e64 s[16:17], v61, v34
	v_cmp_eq_f32_e64 s[18:19], v61, v34
	v_addc_co_u32_e64 v35, s[20:21], v35, v35, s[10:11]
	v_addc_co_u32_e64 v38, s[20:21], v38, v38, s[12:13]
	v_addc_co_u32_e64 v35, s[20:21], v35, v35, s[16:17]
	v_addc_co_u32_e64 v38, s[20:21], v38, v38, s[18:19]
	v_cmp_gt_f32_e64 s[10:11], v62, v34
	v_cmp_eq_f32_e64 s[12:13], v62, v34
	v_cmp_gt_f32_e64 s[16:17], v63, v34
	v_cmp_eq_f32_e64 s[18:19], v63, v34
	v_addc_co_u32_e64 v35, s[20:21], v35, v35, s[10:11]
	v_addc_co_u32_e64 v38, s[20:21], v38, v38, s[12:13]
	v_addc_co_u32_e64 v35, s[20:21], v35, v35, s[16:17]
	v_addc_co_u32_e64 v38, s[20:21], v38, v38, s[18:19]
	ds_read_b128 v[60:63], v65 offset:2096
	s_waitcnt lgkmcnt(6)
	v_cmp_gt_f32_e64 s[10:11], v40, v34
	v_cmp_eq_f32_e64 s[12:13], v40, v34
	v_cmp_gt_f32_e64 s[16:17], v41, v34
	v_cmp_eq_f32_e64 s[18:19], v41, v34
	v_addc_co_u32_e64 v35, s[20:21], v35, v35, s[10:11]
	v_addc_co_u32_e64 v38, s[20:21], v38, v38, s[12:13]
	v_addc_co_u32_e64 v35, s[20:21], v35, v35, s[16:17]
	v_addc_co_u32_e64 v38, s[20:21], v38, v38, s[18:19]
	v_cmp_gt_f32_e64 s[10:11], v42, v34
	v_cmp_eq_f32_e64 s[12:13], v42, v34
	v_cmp_gt_f32_e64 s[16:17], v43, v34
	v_cmp_eq_f32_e64 s[18:19], v43, v34
	v_addc_co_u32_e64 v35, s[20:21], v35, v35, s[10:11]
	v_addc_co_u32_e64 v38, s[20:21], v38, v38, s[12:13]
	v_addc_co_u32_e64 v35, s[20:21], v35, v35, s[16:17]
	v_addc_co_u32_e64 v38, s[20:21], v38, v38, s[18:19]
	ds_read_b128 v[40:43], v65 offset:2112
	s_waitcnt lgkmcnt(6)
; DI void attn_unit(LAS unsigned char* lds, const Args& a, int bg, int qt) {
;     ...
;         for (int it = 0; it < 4; ++it) { const int q = (tid >> 5) + 16 * it;
;             const float v = VAL[q * 32 + j]; int cnt = 0;
; #pragma unroll 8
;             for (int jj = 0; jj < 32; ++jj) { const float ov = VAL[q * 32 + jj]; cnt += ((ov > v) || (ov == v && jj < j)) ? 1 : 0; }
;             const unsigned long long bal = __ballot(cnt < 16);
;             const unsigned mk = ((lane < 32) ? (unsigned)bal : (unsigned)(bal >> 32)) & causal_bits;
;             if ((lane & 31) == 0) MSK[q] = mk; }
	v_cmp_gt_f32_e64 s[10:11], v44, v34
	v_cmp_eq_f32_e64 s[12:13], v44, v34
	v_cmp_gt_f32_e64 s[16:17], v45, v34
	v_cmp_eq_f32_e64 s[18:19], v45, v34
	v_addc_co_u32_e64 v35, s[20:21], v35, v35, s[10:11]
	v_addc_co_u32_e64 v38, s[20:21], v38, v38, s[12:13]
	v_addc_co_u32_e64 v35, s[20:21], v35, v35, s[16:17]
	v_addc_co_u32_e64 v38, s[20:21], v38, v38, s[18:19]
	v_cmp_gt_f32_e64 s[10:11], v46, v34
	v_cmp_eq_f32_e64 s[12:13], v46, v34
	v_cmp_gt_f32_e64 s[16:17], v47, v34
	v_cmp_eq_f32_e64 s[18:19], v47, v34
	v_addc_co_u32_e64 v35, s[20:21], v35, v35, s[10:11]
	v_addc_co_u32_e64 v38, s[20:21], v38, v38, s[12:13]
	v_addc_co_u32_e64 v35, s[20:21], v35, v35, s[16:17]
	v_addc_co_u32_e64 v38, s[20:21], v38, v38, s[18:19]
	ds_read_b128 v[44:47], v65 offset:2128
	v_lshrrev_b32_e64 v39, v98, -1
	v_not_b32_e32 v39, v39
	v_and_b32_e32 v38, v38, v39
	v_bcnt_u32_b32 v35, v35, 0
	v_bcnt_u32_b32 v35, v38, v35
	v_cmp_gt_u32_e32 vcc, 16, v35
	s_and_saveexec_b64 s[10:11], s[6:7]
	s_nop 0
	v_lshrrev_b64 v[38:39], v134, vcc
	v_and_b32_e32 v38, s28, v38
	ds_write_b32 v225, v38
	s_or_b64 exec, exec, s[10:11]
	v_mov_b32_e32 v35, 0
	v_mov_b32_e32 v38, 0
	s_waitcnt lgkmcnt(6)
	v_cmp_gt_f32_e64 s[10:11], v48, v64
	v_cmp_eq_f32_e64 s[12:13], v48, v64
	v_cmp_gt_f32_e64 s[16:17], v49, v64
	v_cmp_eq_f32_e64 s[18:19], v49, v64
	v_addc_co_u32_e64 v35, s[20:21], v35, v35, s[10:11]
	v_addc_co_u32_e64 v38, s[20:21], v38, v38, s[12:13]
	v_addc_co_u32_e64 v35, s[20:21], v35, v35, s[16:17]
	v_addc_co_u32_e64 v38, s[20:21], v38, v38, s[18:19]
	v_cmp_gt_f32_e64 s[10:11], v50, v64
	v_cmp_eq_f32_e64 s[12:13], v50, v64
	v_cmp_gt_f32_e64 s[16:17], v51, v64
	v_cmp_eq_f32_e64 s[18:19], v51, v64
	v_addc_co_u32_e64 v35, s[20:21], v35, v35, s[10:11]
	v_addc_co_u32_e64 v38, s[20:21], v38, v38, s[12:13]
	v_addc_co_u32_e64 v35, s[20:21], v35, v35, s[16:17]
	v_addc_co_u32_e64 v38, s[20:21], v38, v38, s[18:19]
	ds_read_b128 v[48:51], v65 offset:2144
	s_waitcnt lgkmcnt(6)
	v_cmp_gt_f32_e64 s[10:11], v52, v64
	v_cmp_eq_f32_e64 s[12:13], v52, v64
	v_cmp_gt_f32_e64 s[16:17], v53, v64
	v_cmp_eq_f32_e64 s[18:19], v53, v64
	v_addc_co_u32_e64 v35, s[20:21], v35, v35, s[10:11]
	v_addc_co_u32_e64 v38, s[20:21], v38, v38, s[12:13]
	v_addc_co_u32_e64 v35, s[20:21], v35, v35, s[16:17]
	v_addc_co_u32_e64 v38, s[20:21], v38, v38, s[18:19]
	v_cmp_gt_f32_e64 s[10:11], v54, v64
	v_cmp_eq_f32_e64 s[12:13], v54, v64
	v_cmp_gt_f32_e64 s[16:17], v55, v64
	v_cmp_eq_f32_e64 s[18:19], v55, v64
	v_addc_co_u32_e64 v35, s[20:21], v35, v35, s[10:11]
	v_addc_co_u32_e64 v38, s[20:21], v38, v38, s[12:13]
	v_addc_co_u32_e64 v35, s[20:21], v35, v35, s[16:17]
	v_addc_co_u32_e64 v38, s[20:21], v38, v38, s[18:19]
	ds_read_b128 v[52:55], v65 offset:2160
	s_waitcnt lgkmcnt(6)
	v_cmp_gt_f32_e64 s[10:11], v56, v64
	v_cmp_eq_f32_e64 s[12:13], v56, v64
	v_cmp_gt_f32_e64 s[16:17], v57, v64
	v_cmp_eq_f32_e64 s[18:19], v57, v64
	v_addc_co_u32_e64 v35, s[20:21], v35, v35, s[10:11]
	v_addc_co_u32_e64 v38, s[20:21], v38, v38, s[12:13]
	v_addc_co_u32_e64 v35, s[20:21], v35, v35, s[16:17]
	v_addc_co_u32_e64 v38, s[20:21], v38, v38, s[18:19]
	v_cmp_gt_f32_e64 s[10:11], v58, v64
	v_cmp_eq_f32_e64 s[12:13], v58, v64
	v_cmp_gt_f32_e64 s[16:17], v59, v64
	v_cmp_eq_f32_e64 s[18:19], v59, v64
	v_addc_co_u32_e64 v35, s[20:21], v35, v35, s[10:11]
	v_addc_co_u32_e64 v38, s[20:21], v38, v38, s[12:13]
	v_addc_co_u32_e64 v35, s[20:21], v35, v35, s[16:17]
	v_addc_co_u32_e64 v38, s[20:21], v38, v38, s[18:19]
	ds_read_b32 v34, v228
	ds_read_b128 v[56:59], v65 offset:4096
	s_waitcnt lgkmcnt(7)
	v_cmp_gt_f32_e64 s[10:11], v60, v64
	v_cmp_eq_f32_e64 s[12:13], v60, v64
	v_cmp_gt_f32_e64 s[16:17], v61, v64
	v_cmp_eq_f32_e64 s[18:19], v61, v64
	v_addc_co_u32_e64 v35, s[20:21], v35, v35, s[10:11]
	v_addc_co_u32_e64 v38, s[20:21], v38, v38, s[12:13]
	v_addc_co_u32_e64 v35, s[20:21], v35, v35, s[16:17]
	v_addc_co_u32_e64 v38, s[20:21], v38, v38, s[18:19]
	v_cmp_gt_f32_e64 s[10:11], v62, v64
	v_cmp_eq_f32_e64 s[12:13], v62, v64
	v_cmp_gt_f32_e64 s[16:17], v63, v64
	v_cmp_eq_f32_e64 s[18:19], v63, v64
	v_addc_co_u32_e64 v35, s[20:21], v35, v35, s[10:11]
	v_addc_co_u32_e64 v38, s[20:21], v38, v38, s[12:13]
	v_addc_co_u32_e64 v35, s[20:21], v35, v35, s[16:17]
	v_addc_co_u32_e64 v38, s[20:21], v38, v38, s[18:19]
	ds_read_b128 v[60:63], v65 offset:4112
	s_waitcnt lgkmcnt(7)
	v_cmp_gt_f32_e64 s[10:11], v40, v64
	v_cmp_eq_f32_e64 s[12:13], v40, v64
	v_cmp_gt_f32_e64 s[16:17], v41, v64
	v_cmp_eq_f32_e64 s[18:19], v41, v64
	v_addc_co_u32_e64 v35, s[20:21], v35, v35, s[10:11]
	v_addc_co_u32_e64 v38, s[20:21], v38, v38, s[12:13]
	v_addc_co_u32_e64 v35, s[20:21], v35, v35, s[16:17]
	v_addc_co_u32_e64 v38, s[20:21], v38, v38, s[18:19]
	v_cmp_gt_f32_e64 s[10:11], v42, v64
	v_cmp_eq_f32_e64 s[12:13], v42, v64
	v_cmp_gt_f32_e64 s[16:17], v43, v64
	v_cmp_eq_f32_e64 s[18:19], v43, v64
	v_addc_co_u32_e64 v35, s[20:21], v35, v35, s[10:11]
	v_addc_co_u32_e64 v38, s[20:21], v38, v38, s[12:13]
	v_addc_co_u32_e64 v35, s[20:21], v35, v35, s[16:17]
	v_addc_co_u32_e64 v38, s[20:21], v38, v38, s[18:19]
	ds_read_b128 v[40:43], v65 offset:4128
	s_waitcnt lgkmcnt(7)
	v_cmp_gt_f32_e64 s[10:11], v44, v64
	v_cmp_eq_f32_e64 s[12:13], v44, v64
	v_cmp_gt_f32_e64 s[16:17], v45, v64
	v_cmp_eq_f32_e64 s[18:19], v45, v64
	v_addc_co_u32_e64 v35, s[20:21], v35, v35, s[10:11]
	v_addc_co_u32_e64 v38, s[20:21], v38, v38, s[12:13]
	v_addc_co_u32_e64 v35, s[20:21], v35, v35, s[16:17]
	v_addc_co_u32_e64 v38, s[20:21], v38, v38, s[18:19]
	v_cmp_gt_f32_e64 s[10:11], v46, v64
	v_cmp_eq_f32_e64 s[12:13], v46, v64
	v_cmp_gt_f32_e64 s[16:17], v47, v64
	v_cmp_eq_f32_e64 s[18:19], v47, v64
	v_addc_co_u32_e64 v35, s[20:21], v35, v35, s[10:11]
	v_addc_co_u32_e64 v38, s[20:21], v38, v38, s[12:13]
	v_addc_co_u32_e64 v35, s[20:21], v35, v35, s[16:17]
	v_addc_co_u32_e64 v38, s[20:21], v38, v38, s[18:19]
	ds_read_b128 v[44:47], v65 offset:4144
	s_waitcnt lgkmcnt(6)
; DI void attn_unit(LAS unsigned char* lds, const Args& a, int bg, int qt) {
;     ...
;         for (int it = 0; it < 4; ++it) { const int q = (tid >> 5) + 16 * it;
;             const float v = VAL[q * 32 + j]; int cnt = 0;
; #pragma unroll 8
;             for (int jj = 0; jj < 32; ++jj) { const float ov = VAL[q * 32 + jj]; cnt += ((ov > v) || (ov == v && jj < j)) ? 1 : 0; }
;             const unsigned long long bal = __ballot(cnt < 16);
;             const unsigned mk = ((lane < 32) ? (unsigned)bal : (unsigned)(bal >> 32)) & causal_bits;
;             if ((lane & 31) == 0) MSK[q] = mk; }
	v_cmp_gt_f32_e64 s[10:11], v48, v64
	v_cmp_eq_f32_e64 s[12:13], v48, v64
	v_cmp_gt_f32_e64 s[16:17], v49, v64
	v_cmp_eq_f32_e64 s[18:19], v49, v64
	v_addc_co_u32_e64 v35, s[20:21], v35, v35, s[10:11]
	v_addc_co_u32_e64 v38, s[20:21], v38, v38, s[12:13]
	v_addc_co_u32_e64 v35, s[20:21], v35, v35, s[16:17]
	v_addc_co_u32_e64 v38, s[20:21], v38, v38, s[18:19]
	v_cmp_gt_f32_e64 s[10:11], v50, v64
	v_cmp_eq_f32_e64 s[12:13], v50, v64
	v_cmp_gt_f32_e64 s[16:17], v51, v64
	v_cmp_eq_f32_e64 s[18:19], v51, v64
	v_addc_co_u32_e64 v35, s[20:21], v35, v35, s[10:11]
	v_addc_co_u32_e64 v38, s[20:21], v38, v38, s[12:13]
	v_addc_co_u32_e64 v35, s[20:21], v35, v35, s[16:17]
	v_addc_co_u32_e64 v38, s[20:21], v38, v38, s[18:19]
	ds_read_b128 v[48:51], v65 offset:4160
	s_waitcnt lgkmcnt(6)
	v_cmp_gt_f32_e64 s[10:11], v52, v64
	v_cmp_eq_f32_e64 s[12:13], v52, v64
	v_cmp_gt_f32_e64 s[16:17], v53, v64
	v_cmp_eq_f32_e64 s[18:19], v53, v64
	v_addc_co_u32_e64 v35, s[20:21], v35, v35, s[10:11]
	v_addc_co_u32_e64 v38, s[20:21], v38, v38, s[12:13]
	v_addc_co_u32_e64 v35, s[20:21], v35, v35, s[16:17]
	v_addc_co_u32_e64 v38, s[20:21], v38, v38, s[18:19]
	v_cmp_gt_f32_e64 s[10:11], v54, v64
	v_cmp_eq_f32_e64 s[12:13], v54, v64
	v_cmp_gt_f32_e64 s[16:17], v55, v64
	v_cmp_eq_f32_e64 s[18:19], v55, v64
	v_addc_co_u32_e64 v35, s[20:21], v35, v35, s[10:11]
	v_addc_co_u32_e64 v38, s[20:21], v38, v38, s[12:13]
	v_addc_co_u32_e64 v35, s[20:21], v35, v35, s[16:17]
	v_addc_co_u32_e64 v38, s[20:21], v38, v38, s[18:19]
	ds_read_b128 v[52:55], v65 offset:4176
	v_lshrrev_b32_e64 v39, v98, -1
	v_not_b32_e32 v39, v39
	v_and_b32_e32 v38, v38, v39
	v_bcnt_u32_b32 v35, v35, 0
	v_bcnt_u32_b32 v35, v38, v35
	v_cmp_gt_u32_e32 vcc, 16, v35
	s_and_saveexec_b64 s[10:11], s[6:7]
	s_nop 0
	v_lshrrev_b64 v[38:39], v134, vcc
	v_and_b32_e32 v38, s28, v38
	ds_write_b32 v227, v38
	s_or_b64 exec, exec, s[10:11]
	v_mov_b32_e32 v35, 0
	v_mov_b32_e32 v38, 0
	s_waitcnt lgkmcnt(6)
	v_cmp_gt_f32_e64 s[10:11], v56, v34
	v_cmp_eq_f32_e64 s[12:13], v56, v34
	v_cmp_gt_f32_e64 s[16:17], v57, v34
	v_cmp_eq_f32_e64 s[18:19], v57, v34
	v_addc_co_u32_e64 v35, s[20:21], v35, v35, s[10:11]
	v_addc_co_u32_e64 v38, s[20:21], v38, v38, s[12:13]
	v_addc_co_u32_e64 v35, s[20:21], v35, v35, s[16:17]
	v_addc_co_u32_e64 v38, s[20:21], v38, v38, s[18:19]
	v_cmp_gt_f32_e64 s[10:11], v58, v34
	v_cmp_eq_f32_e64 s[12:13], v58, v34
	v_cmp_gt_f32_e64 s[16:17], v59, v34
	v_cmp_eq_f32_e64 s[18:19], v59, v34
	v_addc_co_u32_e64 v35, s[20:21], v35, v35, s[10:11]
	v_addc_co_u32_e64 v38, s[20:21], v38, v38, s[12:13]
	v_addc_co_u32_e64 v35, s[20:21], v35, v35, s[16:17]
	v_addc_co_u32_e64 v38, s[20:21], v38, v38, s[18:19]
	ds_read_b128 v[56:59], v65 offset:4192
	s_waitcnt lgkmcnt(6)
	v_cmp_gt_f32_e64 s[10:11], v60, v34
	v_cmp_eq_f32_e64 s[12:13], v60, v34
	v_cmp_gt_f32_e64 s[16:17], v61, v34
	v_cmp_eq_f32_e64 s[18:19], v61, v34
	v_addc_co_u32_e64 v35, s[20:21], v35, v35, s[10:11]
	v_addc_co_u32_e64 v38, s[20:21], v38, v38, s[12:13]
	v_addc_co_u32_e64 v35, s[20:21], v35, v35, s[16:17]
	v_addc_co_u32_e64 v38, s[20:21], v38, v38, s[18:19]
	v_cmp_gt_f32_e64 s[10:11], v62, v34
	v_cmp_eq_f32_e64 s[12:13], v62, v34
	v_cmp_gt_f32_e64 s[16:17], v63, v34
	v_cmp_eq_f32_e64 s[18:19], v63, v34
	v_addc_co_u32_e64 v35, s[20:21], v35, v35, s[10:11]
	v_addc_co_u32_e64 v38, s[20:21], v38, v38, s[12:13]
	v_addc_co_u32_e64 v35, s[20:21], v35, v35, s[16:17]
	v_addc_co_u32_e64 v38, s[20:21], v38, v38, s[18:19]
	ds_read_b128 v[60:63], v65 offset:4208
	s_waitcnt lgkmcnt(6)
	v_cmp_gt_f32_e64 s[10:11], v40, v34
	v_cmp_eq_f32_e64 s[12:13], v40, v34
	v_cmp_gt_f32_e64 s[16:17], v41, v34
	v_cmp_eq_f32_e64 s[18:19], v41, v34
	v_addc_co_u32_e64 v35, s[20:21], v35, v35, s[10:11]
	v_addc_co_u32_e64 v38, s[20:21], v38, v38, s[12:13]
	v_addc_co_u32_e64 v35, s[20:21], v35, v35, s[16:17]
	v_addc_co_u32_e64 v38, s[20:21], v38, v38, s[18:19]
	v_cmp_gt_f32_e64 s[10:11], v42, v34
	v_cmp_eq_f32_e64 s[12:13], v42, v34
	v_cmp_gt_f32_e64 s[16:17], v43, v34
	v_cmp_eq_f32_e64 s[18:19], v43, v34
	v_addc_co_u32_e64 v35, s[20:21], v35, v35, s[10:11]
	v_addc_co_u32_e64 v38, s[20:21], v38, v38, s[12:13]
	v_addc_co_u32_e64 v35, s[20:21], v35, v35, s[16:17]
	v_addc_co_u32_e64 v38, s[20:21], v38, v38, s[18:19]
	ds_read_b32 v64, v230
	ds_read_b128 v[40:43], v65 offset:6144
	s_waitcnt lgkmcnt(7)
	v_cmp_gt_f32_e64 s[10:11], v44, v34
	v_cmp_eq_f32_e64 s[12:13], v44, v34
	v_cmp_gt_f32_e64 s[16:17], v45, v34
	v_cmp_eq_f32_e64 s[18:19], v45, v34
	v_addc_co_u32_e64 v35, s[20:21], v35, v35, s[10:11]
	v_addc_co_u32_e64 v38, s[20:21], v38, v38, s[12:13]
	v_addc_co_u32_e64 v35, s[20:21], v35, v35, s[16:17]
	v_addc_co_u32_e64 v38, s[20:21], v38, v38, s[18:19]
	v_cmp_gt_f32_e64 s[10:11], v46, v34
	v_cmp_eq_f32_e64 s[12:13], v46, v34
	v_cmp_gt_f32_e64 s[16:17], v47, v34
	v_cmp_eq_f32_e64 s[18:19], v47, v34
	v_addc_co_u32_e64 v35, s[20:21], v35, v35, s[10:11]
	v_addc_co_u32_e64 v38, s[20:21], v38, v38, s[12:13]
	v_addc_co_u32_e64 v35, s[20:21], v35, v35, s[16:17]
	v_addc_co_u32_e64 v38, s[20:21], v38, v38, s[18:19]
	ds_read_b128 v[44:47], v65 offset:6160
	s_waitcnt lgkmcnt(7)
	v_cmp_gt_f32_e64 s[10:11], v48, v34
	v_cmp_eq_f32_e64 s[12:13], v48, v34
	v_cmp_gt_f32_e64 s[16:17], v49, v34
	v_cmp_eq_f32_e64 s[18:19], v49, v34
	v_addc_co_u32_e64 v35, s[20:21], v35, v35, s[10:11]
	v_addc_co_u32_e64 v38, s[20:21], v38, v38, s[12:13]
	v_addc_co_u32_e64 v35, s[20:21], v35, v35, s[16:17]
	v_addc_co_u32_e64 v38, s[20:21], v38, v38, s[18:19]
	v_cmp_gt_f32_e64 s[10:11], v50, v34
	v_cmp_eq_f32_e64 s[12:13], v50, v34
	v_cmp_gt_f32_e64 s[16:17], v51, v34
	v_cmp_eq_f32_e64 s[18:19], v51, v34
	v_addc_co_u32_e64 v35, s[20:21], v35, v35, s[10:11]
	v_addc_co_u32_e64 v38, s[20:21], v38, v38, s[12:13]
	v_addc_co_u32_e64 v35, s[20:21], v35, v35, s[16:17]
	v_addc_co_u32_e64 v38, s[20:21], v38, v38, s[18:19]
	ds_read_b128 v[48:51], v65 offset:6176
	s_waitcnt lgkmcnt(7)
; DI void attn_unit(LAS unsigned char* lds, const Args& a, int bg, int qt) {
;     ...
;         for (int it = 0; it < 4; ++it) { const int q = (tid >> 5) + 16 * it;
;             const float v = VAL[q * 32 + j]; int cnt = 0;
; #pragma unroll 8
;             for (int jj = 0; jj < 32; ++jj) { const float ov = VAL[q * 32 + jj]; cnt += ((ov > v) || (ov == v && jj < j)) ? 1 : 0; }
;             const unsigned long long bal = __ballot(cnt < 16);
;             const unsigned mk = ((lane < 32) ? (unsigned)bal : (unsigned)(bal >> 32)) & causal_bits;
;             if ((lane & 31) == 0) MSK[q] = mk; }
	v_cmp_gt_f32_e64 s[10:11], v52, v34
	v_cmp_eq_f32_e64 s[12:13], v52, v34
	v_cmp_gt_f32_e64 s[16:17], v53, v34
	v_cmp_eq_f32_e64 s[18:19], v53, v34
	v_addc_co_u32_e64 v35, s[20:21], v35, v35, s[10:11]
	v_addc_co_u32_e64 v38, s[20:21], v38, v38, s[12:13]
	v_addc_co_u32_e64 v35, s[20:21], v35, v35, s[16:17]
	v_addc_co_u32_e64 v38, s[20:21], v38, v38, s[18:19]
	v_cmp_gt_f32_e64 s[10:11], v54, v34
	v_cmp_eq_f32_e64 s[12:13], v54, v34
	v_cmp_gt_f32_e64 s[16:17], v55, v34
	v_cmp_eq_f32_e64 s[18:19], v55, v34
	v_addc_co_u32_e64 v35, s[20:21], v35, v35, s[10:11]
	v_addc_co_u32_e64 v38, s[20:21], v38, v38, s[12:13]
	v_addc_co_u32_e64 v35, s[20:21], v35, v35, s[16:17]
	v_addc_co_u32_e64 v38, s[20:21], v38, v38, s[18:19]
	ds_read_b128 v[52:55], v65 offset:6192
	s_waitcnt lgkmcnt(6)
	v_cmp_gt_f32_e64 s[10:11], v56, v34
	v_cmp_eq_f32_e64 s[12:13], v56, v34
	v_cmp_gt_f32_e64 s[16:17], v57, v34
	v_cmp_eq_f32_e64 s[18:19], v57, v34
	v_addc_co_u32_e64 v35, s[20:21], v35, v35, s[10:11]
	v_addc_co_u32_e64 v38, s[20:21], v38, v38, s[12:13]
	v_addc_co_u32_e64 v35, s[20:21], v35, v35, s[16:17]
	v_addc_co_u32_e64 v38, s[20:21], v38, v38, s[18:19]
	v_cmp_gt_f32_e64 s[10:11], v58, v34
	v_cmp_eq_f32_e64 s[12:13], v58, v34
	v_cmp_gt_f32_e64 s[16:17], v59, v34
	v_cmp_eq_f32_e64 s[18:19], v59, v34
	v_addc_co_u32_e64 v35, s[20:21], v35, v35, s[10:11]
	v_addc_co_u32_e64 v38, s[20:21], v38, v38, s[12:13]
	v_addc_co_u32_e64 v35, s[20:21], v35, v35, s[16:17]
	v_addc_co_u32_e64 v38, s[20:21], v38, v38, s[18:19]
	ds_read_b128 v[56:59], v65 offset:6208
	s_waitcnt lgkmcnt(6)
	v_cmp_gt_f32_e64 s[10:11], v60, v34
	v_cmp_eq_f32_e64 s[12:13], v60, v34
	v_cmp_gt_f32_e64 s[16:17], v61, v34
	v_cmp_eq_f32_e64 s[18:19], v61, v34
	v_addc_co_u32_e64 v35, s[20:21], v35, v35, s[10:11]
	v_addc_co_u32_e64 v38, s[20:21], v38, v38, s[12:13]
	v_addc_co_u32_e64 v35, s[20:21], v35, v35, s[16:17]
	v_addc_co_u32_e64 v38, s[20:21], v38, v38, s[18:19]
	v_cmp_gt_f32_e64 s[10:11], v62, v34
	v_cmp_eq_f32_e64 s[12:13], v62, v34
	v_cmp_gt_f32_e64 s[16:17], v63, v34
	v_cmp_eq_f32_e64 s[18:19], v63, v34
	v_addc_co_u32_e64 v35, s[20:21], v35, v35, s[10:11]
	v_addc_co_u32_e64 v38, s[20:21], v38, v38, s[12:13]
	v_addc_co_u32_e64 v35, s[20:21], v35, v35, s[16:17]
	v_addc_co_u32_e64 v38, s[20:21], v38, v38, s[18:19]
	ds_read_b128 v[60:63], v65 offset:6224
	v_lshrrev_b32_e64 v39, v98, -1
	v_not_b32_e32 v39, v39
	v_and_b32_e32 v38, v38, v39
	v_bcnt_u32_b32 v35, v35, 0
	v_bcnt_u32_b32 v35, v38, v35
	v_cmp_gt_u32_e32 vcc, 16, v35
	s_and_saveexec_b64 s[10:11], s[6:7]
	s_nop 0
	v_lshrrev_b64 v[38:39], v134, vcc
	v_and_b32_e32 v38, s28, v38
	ds_write_b32 v229, v38
	s_or_b64 exec, exec, s[10:11]
	v_mov_b32_e32 v35, 0
	v_mov_b32_e32 v38, 0
	s_waitcnt lgkmcnt(6)
	v_cmp_gt_f32_e64 s[10:11], v40, v64
	v_cmp_eq_f32_e64 s[12:13], v40, v64
	v_cmp_gt_f32_e64 s[16:17], v41, v64
	v_cmp_eq_f32_e64 s[18:19], v41, v64
	v_addc_co_u32_e64 v35, s[20:21], v35, v35, s[10:11]
	v_addc_co_u32_e64 v38, s[20:21], v38, v38, s[12:13]
	v_addc_co_u32_e64 v35, s[20:21], v35, v35, s[16:17]
	v_addc_co_u32_e64 v38, s[20:21], v38, v38, s[18:19]
	v_cmp_gt_f32_e64 s[10:11], v42, v64
	v_cmp_eq_f32_e64 s[12:13], v42, v64
	v_cmp_gt_f32_e64 s[16:17], v43, v64
	v_cmp_eq_f32_e64 s[18:19], v43, v64
	v_addc_co_u32_e64 v35, s[20:21], v35, v35, s[10:11]
	v_addc_co_u32_e64 v38, s[20:21], v38, v38, s[12:13]
	v_addc_co_u32_e64 v35, s[20:21], v35, v35, s[16:17]
	v_addc_co_u32_e64 v38, s[20:21], v38, v38, s[18:19]
	ds_read_b128 v[40:43], v65 offset:6240
	s_waitcnt lgkmcnt(6)
	v_cmp_gt_f32_e64 s[10:11], v44, v64
	v_cmp_eq_f32_e64 s[12:13], v44, v64
	v_cmp_gt_f32_e64 s[16:17], v45, v64
	v_cmp_eq_f32_e64 s[18:19], v45, v64
	v_addc_co_u32_e64 v35, s[20:21], v35, v35, s[10:11]
	v_addc_co_u32_e64 v38, s[20:21], v38, v38, s[12:13]
	v_addc_co_u32_e64 v35, s[20:21], v35, v35, s[16:17]
	v_addc_co_u32_e64 v38, s[20:21], v38, v38, s[18:19]
	v_cmp_gt_f32_e64 s[10:11], v46, v64
	v_cmp_eq_f32_e64 s[12:13], v46, v64
	v_cmp_gt_f32_e64 s[16:17], v47, v64
	v_cmp_eq_f32_e64 s[18:19], v47, v64
	v_addc_co_u32_e64 v35, s[20:21], v35, v35, s[10:11]
	v_addc_co_u32_e64 v38, s[20:21], v38, v38, s[12:13]
	v_addc_co_u32_e64 v35, s[20:21], v35, v35, s[16:17]
	v_addc_co_u32_e64 v38, s[20:21], v38, v38, s[18:19]
	ds_read_b128 v[44:47], v65 offset:6256
	s_waitcnt lgkmcnt(6)
	v_cmp_gt_f32_e64 s[10:11], v48, v64
	v_cmp_eq_f32_e64 s[12:13], v48, v64
	v_cmp_gt_f32_e64 s[16:17], v49, v64
	v_cmp_eq_f32_e64 s[18:19], v49, v64
	v_addc_co_u32_e64 v35, s[20:21], v35, v35, s[10:11]
	v_addc_co_u32_e64 v38, s[20:21], v38, v38, s[12:13]
	v_addc_co_u32_e64 v35, s[20:21], v35, v35, s[16:17]
	v_addc_co_u32_e64 v38, s[20:21], v38, v38, s[18:19]
	v_cmp_gt_f32_e64 s[10:11], v50, v64
	v_cmp_eq_f32_e64 s[12:13], v50, v64
	v_cmp_gt_f32_e64 s[16:17], v51, v64
	v_cmp_eq_f32_e64 s[18:19], v51, v64
	v_addc_co_u32_e64 v35, s[20:21], v35, v35, s[10:11]
	v_addc_co_u32_e64 v38, s[20:21], v38, v38, s[12:13]
	v_addc_co_u32_e64 v35, s[20:21], v35, v35, s[16:17]
	v_addc_co_u32_e64 v38, s[20:21], v38, v38, s[18:19]
	s_waitcnt lgkmcnt(5)
	v_cmp_gt_f32_e64 s[10:11], v52, v64
	v_cmp_eq_f32_e64 s[12:13], v52, v64
	v_cmp_gt_f32_e64 s[16:17], v53, v64
	v_cmp_eq_f32_e64 s[18:19], v53, v64
	v_addc_co_u32_e64 v35, s[20:21], v35, v35, s[10:11]
	v_addc_co_u32_e64 v38, s[20:21], v38, v38, s[12:13]
	v_addc_co_u32_e64 v35, s[20:21], v35, v35, s[16:17]
	v_addc_co_u32_e64 v38, s[20:21], v38, v38, s[18:19]
	v_cmp_gt_f32_e64 s[10:11], v54, v64
	v_cmp_eq_f32_e64 s[12:13], v54, v64
	v_cmp_gt_f32_e64 s[16:17], v55, v64
	v_cmp_eq_f32_e64 s[18:19], v55, v64
	v_addc_co_u32_e64 v35, s[20:21], v35, v35, s[10:11]
	v_addc_co_u32_e64 v38, s[20:21], v38, v38, s[12:13]
	v_addc_co_u32_e64 v35, s[20:21], v35, v35, s[16:17]
	v_addc_co_u32_e64 v38, s[20:21], v38, v38, s[18:19]
	s_waitcnt lgkmcnt(4)
; DI void attn_unit(LAS unsigned char* lds, const Args& a, int bg, int qt) {
;     ...
;         for (int it = 0; it < 4; ++it) { const int q = (tid >> 5) + 16 * it;
;             const float v = VAL[q * 32 + j]; int cnt = 0;
; #pragma unroll 8
;             for (int jj = 0; jj < 32; ++jj) { const float ov = VAL[q * 32 + jj]; cnt += ((ov > v) || (ov == v && jj < j)) ? 1 : 0; }
;             const unsigned long long bal = __ballot(cnt < 16);
;             const unsigned mk = ((lane < 32) ? (unsigned)bal : (unsigned)(bal >> 32)) & causal_bits;
;             if ((lane & 31) == 0) MSK[q] = mk; }
;         __syncthreads();
;         if (w == 0) {
;             int ln = lane; asm volatile("" : "+v"(ln));
;             unsigned U = MSK[ln];
; #pragma unroll
;             for (int of = 1; of < 64; of <<= 1) U |= (unsigned)__shfl_xor((int)U, of);
;             const int n = __popc(U), j0 = qt - 8 < 0 ? 0 : qt - 8;
;             if (ln < 32) { if ((U >> ln) & 1u) LIST[__popc(U & ((1u << ln) - 1u))] = ln; }
	v_cmp_gt_f32_e64 s[10:11], v56, v64
	v_cmp_eq_f32_e64 s[12:13], v56, v64
	v_cmp_gt_f32_e64 s[16:17], v57, v64
	v_cmp_eq_f32_e64 s[18:19], v57, v64
	v_addc_co_u32_e64 v35, s[20:21], v35, v35, s[10:11]
	v_addc_co_u32_e64 v38, s[20:21], v38, v38, s[12:13]
	v_addc_co_u32_e64 v35, s[20:21], v35, v35, s[16:17]
	v_addc_co_u32_e64 v38, s[20:21], v38, v38, s[18:19]
	v_cmp_gt_f32_e64 s[10:11], v58, v64
	v_cmp_eq_f32_e64 s[12:13], v58, v64
	v_cmp_gt_f32_e64 s[16:17], v59, v64
	v_cmp_eq_f32_e64 s[18:19], v59, v64
	v_addc_co_u32_e64 v35, s[20:21], v35, v35, s[10:11]
	v_addc_co_u32_e64 v38, s[20:21], v38, v38, s[12:13]
	v_addc_co_u32_e64 v35, s[20:21], v35, v35, s[16:17]
	v_addc_co_u32_e64 v38, s[20:21], v38, v38, s[18:19]
	s_waitcnt lgkmcnt(3)
	v_cmp_gt_f32_e64 s[10:11], v60, v64
	v_cmp_eq_f32_e64 s[12:13], v60, v64
	v_cmp_gt_f32_e64 s[16:17], v61, v64
	v_cmp_eq_f32_e64 s[18:19], v61, v64
	v_addc_co_u32_e64 v35, s[20:21], v35, v35, s[10:11]
	v_addc_co_u32_e64 v38, s[20:21], v38, v38, s[12:13]
	v_addc_co_u32_e64 v35, s[20:21], v35, v35, s[16:17]
	v_addc_co_u32_e64 v38, s[20:21], v38, v38, s[18:19]
	v_cmp_gt_f32_e64 s[10:11], v62, v64
	v_cmp_eq_f32_e64 s[12:13], v62, v64
	v_cmp_gt_f32_e64 s[16:17], v63, v64
	v_cmp_eq_f32_e64 s[18:19], v63, v64
	v_addc_co_u32_e64 v35, s[20:21], v35, v35, s[10:11]
	v_addc_co_u32_e64 v38, s[20:21], v38, v38, s[12:13]
	v_addc_co_u32_e64 v35, s[20:21], v35, v35, s[16:17]
	v_addc_co_u32_e64 v38, s[20:21], v38, v38, s[18:19]
	s_waitcnt lgkmcnt(1)
	v_cmp_gt_f32_e64 s[10:11], v40, v64
	v_cmp_eq_f32_e64 s[12:13], v40, v64
	v_cmp_gt_f32_e64 s[16:17], v41, v64
	v_cmp_eq_f32_e64 s[18:19], v41, v64
	v_addc_co_u32_e64 v35, s[20:21], v35, v35, s[10:11]
	v_addc_co_u32_e64 v38, s[20:21], v38, v38, s[12:13]
	v_addc_co_u32_e64 v35, s[20:21], v35, v35, s[16:17]
	v_addc_co_u32_e64 v38, s[20:21], v38, v38, s[18:19]
	v_cmp_gt_f32_e64 s[10:11], v42, v64
	v_cmp_eq_f32_e64 s[12:13], v42, v64
	v_cmp_gt_f32_e64 s[16:17], v43, v64
	v_cmp_eq_f32_e64 s[18:19], v43, v64
	v_addc_co_u32_e64 v35, s[20:21], v35, v35, s[10:11]
	v_addc_co_u32_e64 v38, s[20:21], v38, v38, s[12:13]
	v_addc_co_u32_e64 v35, s[20:21], v35, v35, s[16:17]
	v_addc_co_u32_e64 v38, s[20:21], v38, v38, s[18:19]
	s_waitcnt lgkmcnt(0)
	v_cmp_gt_f32_e64 s[10:11], v44, v64
	v_cmp_eq_f32_e64 s[12:13], v44, v64
	v_cmp_gt_f32_e64 s[16:17], v45, v64
	v_cmp_eq_f32_e64 s[18:19], v45, v64
	v_addc_co_u32_e64 v35, s[20:21], v35, v35, s[10:11]
	v_addc_co_u32_e64 v38, s[20:21], v38, v38, s[12:13]
	v_addc_co_u32_e64 v35, s[20:21], v35, v35, s[16:17]
	v_addc_co_u32_e64 v38, s[20:21], v38, v38, s[18:19]
	v_cmp_gt_f32_e64 s[10:11], v46, v64
	v_cmp_eq_f32_e64 s[12:13], v46, v64
	v_cmp_gt_f32_e64 s[16:17], v47, v64
	v_cmp_eq_f32_e64 s[18:19], v47, v64
	v_addc_co_u32_e64 v35, s[20:21], v35, v35, s[10:11]
	v_addc_co_u32_e64 v38, s[20:21], v38, v38, s[12:13]
	v_addc_co_u32_e64 v35, s[20:21], v35, v35, s[16:17]
	v_addc_co_u32_e64 v38, s[20:21], v38, v38, s[18:19]
	v_lshrrev_b32_e64 v39, v98, -1
	v_not_b32_e32 v39, v39
	v_and_b32_e32 v38, v38, v39
	v_bcnt_u32_b32 v35, v35, 0
	v_bcnt_u32_b32 v35, v38, v35
	v_cmp_gt_u32_e32 vcc, 16, v35
	s_and_saveexec_b64 s[10:11], s[6:7]
	s_nop 0
	v_lshrrev_b64 v[38:39], v134, vcc
	v_and_b32_e32 v38, s28, v38
	ds_write_b32 v231, v38
	s_or_b64 exec, exec, s[10:11]
	s_cmp_gt_u32 s79, 63
	s_waitcnt lgkmcnt(0)
	s_barrier
	s_cbranch_scc1 .LBB0_871
	v_mov_b32_e32 v35, v146
	v_and_b32_e32 v38, 64, v239
	v_lshl_add_u32 v34, v35, 2, 0
	v_add_u32_e32 v34, 0x1a400, v34
	ds_read_b32 v34, v34
	v_add_u32_e32 v38, 64, v38
	v_xor_b32_e32 v39, 1, v239
	v_cmp_lt_i32_e32 vcc, v39, v38
	v_xor_b32_e32 v40, 2, v239
	s_nop 0
	v_cndmask_b32_e32 v39, v239, v39, vcc
	v_lshlrev_b32_e32 v39, 2, v39
	s_waitcnt lgkmcnt(0)
	ds_bpermute_b32 v39, v39, v34
	v_cmp_lt_i32_e32 vcc, v40, v38
	s_waitcnt lgkmcnt(0)
	v_or_b32_e32 v34, v39, v34
	v_cndmask_b32_e32 v39, v239, v40, vcc
	v_lshlrev_b32_e32 v39, 2, v39
	ds_bpermute_b32 v39, v39, v34
	v_xor_b32_e32 v40, 4, v239
	v_cmp_lt_i32_e32 vcc, v40, v38
	s_waitcnt lgkmcnt(0)
	v_or_b32_e32 v34, v39, v34
	v_cndmask_b32_e32 v39, v239, v40, vcc
	v_lshlrev_b32_e32 v39, 2, v39
	ds_bpermute_b32 v39, v39, v34
	v_xor_b32_e32 v40, 8, v239
	v_cmp_lt_i32_e32 vcc, v40, v38
	s_waitcnt lgkmcnt(0)
	v_or_b32_e32 v34, v39, v34
	v_cndmask_b32_e32 v39, v239, v40, vcc
	v_lshlrev_b32_e32 v39, 2, v39
	ds_bpermute_b32 v39, v39, v34
	v_xor_b32_e32 v40, 16, v239
	v_cmp_lt_i32_e32 vcc, v40, v38
	s_waitcnt lgkmcnt(0)
	v_or_b32_e32 v34, v39, v34
	v_cndmask_b32_e32 v39, v239, v40, vcc
	v_lshlrev_b32_e32 v39, 2, v39
	ds_bpermute_b32 v39, v39, v34
	v_xor_b32_e32 v40, 32, v239
	v_cmp_lt_i32_e32 vcc, v40, v38
	s_waitcnt lgkmcnt(0)
	v_or_b32_e32 v34, v39, v34
	v_cndmask_b32_e32 v38, v239, v40, vcc
	v_lshlrev_b32_e32 v38, 2, v38
	ds_bpermute_b32 v38, v38, v34
	v_cmp_lt_i32_e32 vcc, 31, v35
	s_waitcnt lgkmcnt(0)
	v_or_b32_e32 v38, v38, v34
	v_bcnt_u32_b32 v34, v38, 0
	s_and_saveexec_b64 s[10:11], vcc
	s_xor_b64 s[10:11], exec, s[10:11]
	s_cbranch_execnz .LBB0_878
	s_andn2_saveexec_b64 s[10:11], s[10:11]
	s_cbranch_execnz .LBB0_881
